# delta scan: q.S output reductions batched 4 steps at a time (reduce-scatter with v_cndmask + DPP row_ror), parked per 16-step block
# speedup vs baseline: 1.0939x; 1.0042x over previous
;   __device__ __forceinline__ unsigned char* W() const { return (unsigned char*)(GAS unsigned char*)ws; }
; template <int MIX, int VN> ...
;   if (t < T) {
;     const bf16_t* pr = Pb + (size_t)t * DINP;
;     const int vbase = (MIX == 0) ? 512 : (MIX == 1) ? 1544 : (MIX == 2) ? 2312 : 3352;
;     if (VN == 4) R2 = *(const uint2*)(pr + vbase + h * 64 + vcol);
;     else R2.x = *(const unsigned*)(pr + vbase + h * 64 + vcol);
;     if (MIX == 0) {
;       R0 = *(const uint4*)(pr + 0 + h * 64 + sub * 8); R1 = *(const uint4*)(pr + 256 + h * 64 + sub * 8);
;       ex0 = pr[768 + h]; ex1 = pr[772 + h];
;     } else if (MIX == 1) {
; template <int MIX>
; __device__ __forceinline__ void scan_part(const Params& p, const int layer, const int smp, const int b0, const int bstep, const int bend, const int h, const int part, char* lds, const int tid) {
;     ...
;     __syncthreads();
;     if (MIX == 0 && t0 + 32 < T) {
;       if (tid < 3 * RS / 8) { const uint4 v = *(const uint4*)(rawb + 32 * RS + tid * 8); *(uint4*)(rawb + tid * 8) = v; }
;     }
;     if (t0 + 32 < T) load_chunk_fn<MIX, VN>(p.W(), Pb, t0 + 32 + tt, T, h, vcol, sub, posb, R0, R1, R2, R4, R5, ex0, ex1);
;     {
;       StepIn<MIX, KPL> sa, sb;
;       float osave = 0.f;
;       load_step<MIX, KPL>(qkdv, scal, 0, kg, col, sa);
;       for (int t = 0; t < ntok; t += 2) {
;         load_step<MIX, KPL>(qkdv, scal, t + 1, kg, col, sb);
;         __builtin_amdgcn_sched_barrier(0);
;         const float oa = do_step<MIX, KPL, KG>(sa, S, gam);
;         osave = (kg == (t & (KG - 1))) ? oa : osave;
;         load_step<MIX, KPL>(qkdv, scal, min(t + 2, ntok - 1), kg, col, sa);
.LBB0_426:
	s_or_b64 exec, exec, s[50:51]
	s_cmpk_lt_u32 s23, 0x7f0
	s_cselect_b64 s[50:51], -1, 0
	s_cmpk_gt_u32 s23, 0x7ef
	s_cselect_b64 s[44:45], -1, 0
	s_and_b64 s[56:57], s[40:41], s[50:51]
	s_waitcnt lgkmcnt(0)
	s_barrier
	v_mov_b32_e32 v211, v145
	v_mov_b32_e32 v212, v136
	v_mov_b32_e32 v213, 0
	v_and_b32_e32 v214, 3, v135
	v_lshl_add_u32 v214, v214, 6, v136
	ds_read_b128 v[92:95], v211 offset:256
	ds_read_b64 v[106:107], v213 offset:36864
	ds_read_b32 v182, v212 offset:768
	ds_read_b128 v[76:79], v211
	ds_read_b128 v[174:177], v211 offset:1280
	ds_read_b64 v[154:155], v213 offset:36880
	ds_read_b32 v188, v212 offset:1792
	ds_read_b128 v[80:83], v211 offset:1024
	s_andn2_b64 vcc, exec, s[50:51]
	s_add_i32 s27, s23, 32
	s_cbranch_vccnz .LBB0_432
	v_add_u32_e32 v0, s27, v131
	s_movk_i32 s29, 0x810
	v_cmp_gt_i32_e32 vcc, s29, v0
	s_and_saveexec_b64 s[50:51], vcc
	s_cbranch_execz .LBB0_431
	s_waitcnt vmcnt(3)
	v_mov_b64_e32 v[68:69], s[2:3]
	v_mad_i64_i32 v[0:1], s[52:53], v0, s68, v[68:69]
	v_lshl_add_u64 v[68:69], s[34:35], 1, v[0:1]
	v_mov_b32_e32 v97, v3
	s_waitcnt vmcnt(0)
	v_mov_b32_e32 v99, v3
	v_readlane_b32 s52, v254, 17
	v_lshl_add_u64 v[70:71], v[68:69], 0, v[96:97]
	v_lshl_add_u64 v[72:73], v[68:69], 0, v[98:99]
	v_readlane_b32 s53, v254, 18
	s_lshl_b32 s52, s46, 1
	global_load_dword v97, v[70:71], off offset:1024
	s_nop 0
	global_load_dwordx4 v[68:71], v[72:73], off
	v_lshl_add_u64 v[0:1], v[0:1], 0, s[52:53]
	global_load_dwordx4 v[72:75], v[72:73], off offset:512
	s_nop 0
	global_load_ushort v133, v[0:1], off offset:1536
	global_load_ushort v99, v[0:1], off offset:1544
	s_mov_b32 s29, s53
	v_writelane_b32 v254, s28, 17
	s_nop 1
	v_writelane_b32 v254, s29, 18

; template <int KG> __device__ __forceinline__ float redKG(float x) { x = red8d(x); if (KG == 16) x += dpp_rm(x); return x; }
; template <int MIX, int KPL>
; __device__ __forceinline__ void load_step(const float* qkdv, const float* scal, int t, int kg, int col, StepIn<MIX, KPL>& s) {
;   const float* base = qkdv + t * 256;
; #pragma unroll
;   for (int i = 0; i < KPL; i += 4) {
;     const f32x4 a = *(const f32x4*)(base + kg * KPL + i), b = *(const f32x4*)(base + 64 + kg * KPL + i);
;     s.q[i] = a[0]; s.q[i + 1] = a[1]; s.q[i + 2] = a[2]; s.q[i + 3] = a[3];
;     s.k[i] = b[0]; s.k[i + 1] = b[1]; s.k[i + 2] = b[2]; s.k[i + 3] = b[3];
;     if (MIX == 1 || MIX == 2) { const f32x4 d = *(const f32x4*)(base + 128 + kg * KPL + i); s.d[i] = d[0]; s.d[i + 1] = d[1]; s.d[i + 2] = d[2]; s.d[i + 3] = d[3]; }
;   }
;   s.v = base[192 + col];
;   if (MIX == 0) { const f32x4 c = *(const f32x4*)(scal + t * 4); s.a = c[0]; s.be = c[1]; s.qk = c[2]; }
; }
; template <int MIX, int KPL, int KG>
; __device__ __forceinline__ float do_step(const StepIn<MIX, KPL>& s, float (&S)[KPL], const float gam) {
;   if (MIX == 0) {
;     float kS0 = 0.f, kS1 = 0.f, qS0 = 0.f, qS1 = 0.f;
; #pragma unroll
;     for (int i = 0; i < KPL; i += 2) { kS0 += s.k[i] * S[i]; kS1 += s.k[i + 1] * S[i + 1]; qS0 += s.q[i] * S[i]; qS1 += s.q[i + 1] * S[i + 1]; }
;     const float kS = redKG<KG>(kS0 + kS1), qS = redKG<KG>(qS0 + qS1);
;     const float w = s.be * (s.v - s.a * kS);
; #pragma unroll
;     for (int i = 0; i < KPL; ++i) S[i] = s.a * S[i] + s.k[i] * w;
;     return s.a * qS + s.qk * w;
; template <int MIX>
; __device__ __forceinline__ void scan_part(const Params& p, const int layer, const int smp, const int b0, const int bstep, const int bend, const int h, const int part, char* lds, const int tid) {
;     ...
;       for (int t = 0; t < ntok; t += 2) {
;         load_step<MIX, KPL>(qkdv, scal, t + 1, kg, col, sb);
;         __builtin_amdgcn_sched_barrier(0);
;         const float oa = do_step<MIX, KPL, KG>(sa, S, gam);
;         osave = (kg == (t & (KG - 1))) ? oa : osave;
;         load_step<MIX, KPL>(qkdv, scal, min(t + 2, ntok - 1), kg, col, sa);
;         __builtin_amdgcn_sched_barrier(0);
;         const float ob = do_step<MIX, KPL, KG>(sb, S, gam);
;         osave = (kg == ((t + 1) & (KG - 1))) ? ob : osave;
;         if (((t + 2) & (KG - 1)) == 0) obuf[(t + 2 - KG + kg) * CW + col] = osave;
.LBB0_432:
	s_lshr_b32 s50, s26, 4
	s_mov_b32 s52, 0xaaaaaaaa
	s_mov_b32 s53, 0xaaaaaaaa
	s_mov_b32 s54, 0xcccccccc
	s_mov_b32 s55, 0xcccccccc
.Lscan0p_blk:
	s_waitcnt lgkmcnt(4)
	v_pk_mul_f32 v[192:193], v[92:93], v[104:105]
	v_pk_fma_f32 v[192:193], v[94:95], v[102:103], v[192:193]
	v_add_f32_e32 v203, v192, v193
	v_pk_mul_f32 v[194:195], v[104:105], v[106:107] op_sel_hi:[1,0]
	v_pk_mul_f32 v[196:197], v[102:103], v[106:107] op_sel_hi:[1,0]
	v_add_f32_dpp v203, v203, v203 quad_perm:[1,0,3,2] row_mask:0xf bank_mask:0xf bound_ctrl:1
	ds_read_b128 v[178:181], v211 offset:2304
	ds_read_b64 v[158:159], v213 offset:36896
	v_add_f32_dpp v203, v203, v203 quad_perm:[2,3,0,1] row_mask:0xf bank_mask:0xf bound_ctrl:1
	ds_read_b32 v189, v212 offset:2816
	ds_read_b128 v[184:187], v211 offset:3328
	v_add_f32_dpp v203, v203, v203 row_half_mirror row_mask:0xf bank_mask:0xf bound_ctrl:1
	ds_read_b64 v[168:169], v213 offset:36912
	ds_read_b32 v190, v212 offset:3840
	v_add_f32_dpp v203, v203, v203 row_mirror row_mask:0xf bank_mask:0xf bound_ctrl:1
	v_fma_f32 v204, -v106, v203, v182
	v_mul_f32_e32 v206, v107, v204
	v_pk_fma_f32 v[104:105], v[92:93], v[206:207], v[194:195] op_sel_hi:[1,0,1]
	v_pk_fma_f32 v[102:103], v[94:95], v[206:207], v[196:197] op_sel_hi:[1,0,1]
	s_waitcnt lgkmcnt(4)
	v_pk_mul_f32 v[192:193], v[174:175], v[104:105]
	v_pk_fma_f32 v[192:193], v[176:177], v[102:103], v[192:193]
	v_add_f32_e32 v203, v192, v193
	v_pk_mul_f32 v[198:199], v[76:77], v[104:105]
	v_pk_mul_f32 v[194:195], v[104:105], v[154:155] op_sel_hi:[1,0]
	v_add_f32_dpp v203, v203, v203 quad_perm:[1,0,3,2] row_mask:0xf bank_mask:0xf bound_ctrl:1
	v_pk_fma_f32 v[198:199], v[78:79], v[102:103], v[198:199]
	v_pk_mul_f32 v[196:197], v[102:103], v[154:155] op_sel_hi:[1,0]
	v_add_f32_dpp v203, v203, v203 quad_perm:[2,3,0,1] row_mask:0xf bank_mask:0xf bound_ctrl:1
	ds_read_b128 v[84:87], v211 offset:2048
	ds_read_b128 v[92:95], v211 offset:4352
	v_add_f32_dpp v203, v203, v203 row_half_mirror row_mask:0xf bank_mask:0xf bound_ctrl:1
	v_add_f32_e32 v215, v198, v199
	ds_read_b64 v[106:107], v213 offset:36928
	v_add_f32_dpp v203, v203, v203 row_mirror row_mask:0xf bank_mask:0xf bound_ctrl:1
	v_fma_f32 v204, -v154, v203, v188
	v_mul_f32_e32 v206, v155, v204
	v_pk_fma_f32 v[104:105], v[174:175], v[206:207], v[194:195] op_sel_hi:[1,0,1]
	v_pk_fma_f32 v[102:103], v[176:177], v[206:207], v[196:197] op_sel_hi:[1,0,1]
	v_pk_mul_f32 v[192:193], v[178:179], v[104:105]
	v_pk_fma_f32 v[192:193], v[180:181], v[102:103], v[192:193]
	v_add_f32_e32 v203, v192, v193
	v_pk_mul_f32 v[200:201], v[80:81], v[104:105]
	v_pk_mul_f32 v[194:195], v[104:105], v[158:159] op_sel_hi:[1,0]
	v_add_f32_dpp v203, v203, v203 quad_perm:[1,0,3,2] row_mask:0xf bank_mask:0xf bound_ctrl:1
	v_pk_fma_f32 v[200:201], v[82:83], v[102:103], v[200:201]
	v_pk_mul_f32 v[196:197], v[102:103], v[158:159] op_sel_hi:[1,0]
	v_add_f32_dpp v203, v203, v203 quad_perm:[2,3,0,1] row_mask:0xf bank_mask:0xf bound_ctrl:1
	ds_read_b32 v182, v212 offset:4864
	ds_read_b128 v[88:91], v211 offset:3072
	v_add_f32_dpp v203, v203, v203 row_half_mirror row_mask:0xf bank_mask:0xf bound_ctrl:1
	ds_read_b128 v[174:177], v211 offset:5376
	v_add_f32_e32 v216, v200, v201
	v_add_f32_dpp v203, v203, v203 row_mirror row_mask:0xf bank_mask:0xf bound_ctrl:1
	s_waitcnt lgkmcnt(3)
	v_fma_f32 v204, -v158, v203, v189
	v_mul_f32_e32 v206, v159, v204
	v_pk_fma_f32 v[104:105], v[178:179], v[206:207], v[194:195] op_sel_hi:[1,0,1]
	v_pk_fma_f32 v[102:103], v[180:181], v[206:207], v[196:197] op_sel_hi:[1,0,1]
	v_pk_mul_f32 v[192:193], v[184:185], v[104:105]
	v_pk_fma_f32 v[192:193], v[186:187], v[102:103], v[192:193]
	v_add_f32_e32 v203, v192, v193
	v_pk_mul_f32 v[198:199], v[84:85], v[104:105]
	v_pk_mul_f32 v[194:195], v[104:105], v[168:169] op_sel_hi:[1,0]
	v_add_f32_dpp v203, v203, v203 quad_perm:[1,0,3,2] row_mask:0xf bank_mask:0xf bound_ctrl:1
	v_pk_fma_f32 v[198:199], v[86:87], v[102:103], v[198:199]
	v_pk_mul_f32 v[196:197], v[102:103], v[168:169] op_sel_hi:[1,0]
	v_add_f32_dpp v203, v203, v203 quad_perm:[2,3,0,1] row_mask:0xf bank_mask:0xf bound_ctrl:1
	ds_read_b64 v[154:155], v213 offset:36944
	ds_read_b32 v188, v212 offset:5888
	v_add_f32_dpp v203, v203, v203 row_half_mirror row_mask:0xf bank_mask:0xf bound_ctrl:1
	ds_read_b128 v[76:79], v211 offset:4096
	ds_read_b128 v[178:181], v211 offset:6400
	v_add_f32_dpp v203, v203, v203 row_mirror row_mask:0xf bank_mask:0xf bound_ctrl:1
	v_fma_f32 v204, -v168, v203, v190
	v_mul_f32_e32 v206, v169, v204
	v_pk_fma_f32 v[104:105], v[184:185], v[206:207], v[194:195] op_sel_hi:[1,0,1]
	v_pk_fma_f32 v[102:103], v[186:187], v[206:207], v[196:197] op_sel_hi:[1,0,1]
	v_pk_mul_f32 v[192:193], v[92:93], v[104:105]
	v_pk_fma_f32 v[192:193], v[94:95], v[102:103], v[192:193]
	v_add_f32_e32 v203, v192, v193
	s_waitcnt lgkmcnt(2)
	v_pk_mul_f32 v[200:201], v[88:89], v[104:105]
	v_pk_mul_f32 v[194:195], v[104:105], v[106:107] op_sel_hi:[1,0]
	v_add_f32_dpp v203, v203, v203 quad_perm:[1,0,3,2] row_mask:0xf bank_mask:0xf bound_ctrl:1
	v_pk_fma_f32 v[200:201], v[90:91], v[102:103], v[200:201]
	v_pk_mul_f32 v[196:197], v[102:103], v[106:107] op_sel_hi:[1,0]
	v_add_f32_dpp v203, v203, v203 quad_perm:[2,3,0,1] row_mask:0xf bank_mask:0xf bound_ctrl:1
	v_add_f32_e32 v217, v198, v199
	ds_read_b64 v[158:159], v213 offset:36960
	v_add_f32_dpp v203, v203, v203 row_half_mirror row_mask:0xf bank_mask:0xf bound_ctrl:1
	ds_read_b32 v189, v212 offset:6912
	ds_read_b128 v[80:83], v211 offset:5120
	v_add_f32_dpp v203, v203, v203 row_mirror row_mask:0xf bank_mask:0xf bound_ctrl:1
	v_fma_f32 v204, -v106, v203, v182
	v_mul_f32_e32 v206, v107, v204
	v_pk_fma_f32 v[104:105], v[92:93], v[206:207], v[194:195] op_sel_hi:[1,0,1]
	v_pk_fma_f32 v[102:103], v[94:95], v[206:207], v[196:197] op_sel_hi:[1,0,1]
	v_pk_mul_f32 v[192:193], v[174:175], v[104:105]
	v_pk_fma_f32 v[192:193], v[176:177], v[102:103], v[192:193]
	v_add_f32_e32 v203, v192, v193
	s_waitcnt lgkmcnt(2)
; template <int KG> __device__ __forceinline__ float redKG(float x) { x = red8d(x); if (KG == 16) x += dpp_rm(x); return x; }
; template <int MIX, int KPL>
; __device__ __forceinline__ void load_step(const float* qkdv, const float* scal, int t, int kg, int col, StepIn<MIX, KPL>& s) {
;   const float* base = qkdv + t * 256;
; #pragma unroll
;   for (int i = 0; i < KPL; i += 4) {
;     const f32x4 a = *(const f32x4*)(base + kg * KPL + i), b = *(const f32x4*)(base + 64 + kg * KPL + i);
;     s.q[i] = a[0]; s.q[i + 1] = a[1]; s.q[i + 2] = a[2]; s.q[i + 3] = a[3];
;     s.k[i] = b[0]; s.k[i + 1] = b[1]; s.k[i + 2] = b[2]; s.k[i + 3] = b[3];
;     if (MIX == 1 || MIX == 2) { const f32x4 d = *(const f32x4*)(base + 128 + kg * KPL + i); s.d[i] = d[0]; s.d[i + 1] = d[1]; s.d[i + 2] = d[2]; s.d[i + 3] = d[3]; }
;   }
;   s.v = base[192 + col];
;   if (MIX == 0) { const f32x4 c = *(const f32x4*)(scal + t * 4); s.a = c[0]; s.be = c[1]; s.qk = c[2]; }
; }
; template <int MIX, int KPL, int KG>
; __device__ __forceinline__ float do_step(const StepIn<MIX, KPL>& s, float (&S)[KPL], const float gam) {
;   if (MIX == 0) {
;     float kS0 = 0.f, kS1 = 0.f, qS0 = 0.f, qS1 = 0.f;
; #pragma unroll
;     for (int i = 0; i < KPL; i += 2) { kS0 += s.k[i] * S[i]; kS1 += s.k[i + 1] * S[i + 1]; qS0 += s.q[i] * S[i]; qS1 += s.q[i + 1] * S[i + 1]; }
;     const float kS = redKG<KG>(kS0 + kS1), qS = redKG<KG>(qS0 + qS1);
;     const float w = s.be * (s.v - s.a * kS);
; #pragma unroll
;     for (int i = 0; i < KPL; ++i) S[i] = s.a * S[i] + s.k[i] * w;
;     return s.a * qS + s.qk * w;
; template <int MIX>
; __device__ __forceinline__ void scan_part(const Params& p, const int layer, const int smp, const int b0, const int bstep, const int bend, const int h, const int part, char* lds, const int tid) {
;     ...
;       for (int t = 0; t < ntok; t += 2) {
;         load_step<MIX, KPL>(qkdv, scal, t + 1, kg, col, sb);
;         __builtin_amdgcn_sched_barrier(0);
;         const float oa = do_step<MIX, KPL, KG>(sa, S, gam);
;         osave = (kg == (t & (KG - 1))) ? oa : osave;
;         load_step<MIX, KPL>(qkdv, scal, min(t + 2, ntok - 1), kg, col, sa);
;         __builtin_amdgcn_sched_barrier(0);
;         const float ob = do_step<MIX, KPL, KG>(sb, S, gam);
;         osave = (kg == ((t + 1) & (KG - 1))) ? ob : osave;
;         if (((t + 2) & (KG - 1)) == 0) obuf[(t + 2 - KG + kg) * CW + col] = osave;
	v_pk_mul_f32 v[198:199], v[76:77], v[104:105]
	v_pk_mul_f32 v[194:195], v[104:105], v[154:155] op_sel_hi:[1,0]
	v_add_f32_dpp v203, v203, v203 quad_perm:[1,0,3,2] row_mask:0xf bank_mask:0xf bound_ctrl:1
	v_pk_fma_f32 v[198:199], v[78:79], v[102:103], v[198:199]
	v_pk_mul_f32 v[196:197], v[102:103], v[154:155] op_sel_hi:[1,0]
	v_add_f32_dpp v203, v203, v203 quad_perm:[2,3,0,1] row_mask:0xf bank_mask:0xf bound_ctrl:1
	ds_read_b128 v[184:187], v211 offset:7424
	v_add_f32_e32 v218, v200, v201
	v_add_f32_dpp v203, v203, v203 row_half_mirror row_mask:0xf bank_mask:0xf bound_ctrl:1
	ds_read_b64 v[168:169], v213 offset:36976
	ds_read_b32 v190, v212 offset:7936
	v_add_f32_dpp v203, v203, v203 row_mirror row_mask:0xf bank_mask:0xf bound_ctrl:1
	v_fma_f32 v204, -v154, v203, v188
	v_mul_f32_e32 v206, v155, v204
	v_pk_fma_f32 v[104:105], v[174:175], v[206:207], v[194:195] op_sel_hi:[1,0,1]
	v_pk_fma_f32 v[102:103], v[176:177], v[206:207], v[196:197] op_sel_hi:[1,0,1]
	v_pk_mul_f32 v[192:193], v[178:179], v[104:105]
	v_pk_fma_f32 v[192:193], v[180:181], v[102:103], v[192:193]
	v_add_f32_e32 v203, v192, v193
	s_waitcnt lgkmcnt(2)
	v_pk_mul_f32 v[200:201], v[80:81], v[104:105]
	v_pk_mul_f32 v[194:195], v[104:105], v[158:159] op_sel_hi:[1,0]
	v_add_f32_dpp v203, v203, v203 quad_perm:[1,0,3,2] row_mask:0xf bank_mask:0xf bound_ctrl:1
	v_pk_fma_f32 v[200:201], v[82:83], v[102:103], v[200:201]
	v_pk_mul_f32 v[196:197], v[102:103], v[158:159] op_sel_hi:[1,0]
	v_add_f32_dpp v203, v203, v203 quad_perm:[2,3,0,1] row_mask:0xf bank_mask:0xf bound_ctrl:1
	ds_read_b128 v[84:87], v211 offset:6144
	ds_read_b128 v[92:95], v211 offset:8448
	v_add_f32_dpp v203, v203, v203 row_half_mirror row_mask:0xf bank_mask:0xf bound_ctrl:1
	v_add_f32_e32 v219, v198, v199
	ds_read_b64 v[106:107], v213 offset:36992
	v_add_f32_dpp v203, v203, v203 row_mirror row_mask:0xf bank_mask:0xf bound_ctrl:1
	v_fma_f32 v204, -v158, v203, v189
	v_mul_f32_e32 v206, v159, v204
	v_pk_fma_f32 v[104:105], v[178:179], v[206:207], v[194:195] op_sel_hi:[1,0,1]
	v_pk_fma_f32 v[102:103], v[180:181], v[206:207], v[196:197] op_sel_hi:[1,0,1]
	v_pk_mul_f32 v[192:193], v[184:185], v[104:105]
	v_pk_fma_f32 v[192:193], v[186:187], v[102:103], v[192:193]
	v_add_f32_e32 v203, v192, v193
	s_waitcnt lgkmcnt(1)
	v_pk_mul_f32 v[194:195], v[104:105], v[168:169] op_sel_hi:[1,0]
	v_pk_mul_f32 v[198:199], v[84:85], v[104:105]
	v_add_f32_dpp v203, v203, v203 quad_perm:[1,0,3,2] row_mask:0xf bank_mask:0xf bound_ctrl:1
	v_pk_fma_f32 v[198:199], v[86:87], v[102:103], v[198:199]
	v_pk_mul_f32 v[196:197], v[102:103], v[168:169] op_sel_hi:[1,0]
	v_add_f32_dpp v203, v203, v203 quad_perm:[2,3,0,1] row_mask:0xf bank_mask:0xf bound_ctrl:1
	ds_read_b32 v182, v212 offset:8960
	ds_read_b128 v[88:91], v211 offset:7168
	v_add_f32_dpp v203, v203, v203 row_half_mirror row_mask:0xf bank_mask:0xf bound_ctrl:1
	ds_read_b128 v[174:177], v211 offset:9472
	v_add_f32_e32 v220, v200, v201
	v_add_f32_dpp v203, v203, v203 row_mirror row_mask:0xf bank_mask:0xf bound_ctrl:1
	v_fma_f32 v204, -v168, v203, v190
	v_mul_f32_e32 v206, v169, v204
	v_pk_fma_f32 v[104:105], v[184:185], v[206:207], v[194:195] op_sel_hi:[1,0,1]
	v_pk_fma_f32 v[102:103], v[186:187], v[206:207], v[196:197] op_sel_hi:[1,0,1]
	v_pk_mul_f32 v[192:193], v[92:93], v[104:105]
	v_pk_fma_f32 v[192:193], v[94:95], v[102:103], v[192:193]
	v_add_f32_e32 v203, v192, v193
	s_waitcnt lgkmcnt(1)
	v_pk_mul_f32 v[194:195], v[104:105], v[106:107] op_sel_hi:[1,0]
	v_pk_mul_f32 v[196:197], v[102:103], v[106:107] op_sel_hi:[1,0]
	v_add_f32_dpp v203, v203, v203 quad_perm:[1,0,3,2] row_mask:0xf bank_mask:0xf bound_ctrl:1
	v_pk_mul_f32 v[200:201], v[88:89], v[104:105]
	v_pk_fma_f32 v[200:201], v[90:91], v[102:103], v[200:201]
	v_add_f32_dpp v203, v203, v203 quad_perm:[2,3,0,1] row_mask:0xf bank_mask:0xf bound_ctrl:1
	ds_read_b64 v[154:155], v213 offset:37008
	ds_read_b32 v188, v212 offset:9984
	v_add_f32_dpp v203, v203, v203 row_half_mirror row_mask:0xf bank_mask:0xf bound_ctrl:1
	ds_read_b128 v[76:79], v211 offset:8192
	ds_read_b128 v[178:181], v211 offset:10496
	v_add_f32_dpp v203, v203, v203 row_mirror row_mask:0xf bank_mask:0xf bound_ctrl:1
	v_fma_f32 v204, -v106, v203, v182
	v_mul_f32_e32 v206, v107, v204
	v_pk_fma_f32 v[104:105], v[92:93], v[206:207], v[194:195] op_sel_hi:[1,0,1]
	v_pk_fma_f32 v[102:103], v[94:95], v[206:207], v[196:197] op_sel_hi:[1,0,1]
	s_waitcnt lgkmcnt(4)
	v_pk_mul_f32 v[192:193], v[174:175], v[104:105]
	v_pk_fma_f32 v[192:193], v[176:177], v[102:103], v[192:193]
	v_add_f32_e32 v203, v192, v193
	v_add_f32_e32 v221, v198, v199
	s_waitcnt lgkmcnt(1)
	v_pk_mul_f32 v[194:195], v[104:105], v[154:155] op_sel_hi:[1,0]
	v_add_f32_dpp v203, v203, v203 quad_perm:[1,0,3,2] row_mask:0xf bank_mask:0xf bound_ctrl:1
	v_pk_mul_f32 v[196:197], v[102:103], v[154:155] op_sel_hi:[1,0]
	v_pk_mul_f32 v[198:199], v[76:77], v[104:105]
	v_add_f32_dpp v203, v203, v203 quad_perm:[2,3,0,1] row_mask:0xf bank_mask:0xf bound_ctrl:1
	v_pk_fma_f32 v[198:199], v[78:79], v[102:103], v[198:199]
	ds_read_b64 v[158:159], v213 offset:37024
	v_add_f32_dpp v203, v203, v203 row_half_mirror row_mask:0xf bank_mask:0xf bound_ctrl:1
	ds_read_b32 v189, v212 offset:11008
	ds_read_b128 v[80:83], v211 offset:9216
	v_add_f32_dpp v203, v203, v203 row_mirror row_mask:0xf bank_mask:0xf bound_ctrl:1
	v_fma_f32 v204, -v154, v203, v188
	v_mul_f32_e32 v206, v155, v204
	v_pk_fma_f32 v[104:105], v[174:175], v[206:207], v[194:195] op_sel_hi:[1,0,1]
	v_pk_fma_f32 v[102:103], v[176:177], v[206:207], v[196:197] op_sel_hi:[1,0,1]
	s_waitcnt lgkmcnt(3)
; template <int KG> __device__ __forceinline__ float redKG(float x) { x = red8d(x); if (KG == 16) x += dpp_rm(x); return x; }
; template <int MIX, int KPL>
; __device__ __forceinline__ void load_step(const float* qkdv, const float* scal, int t, int kg, int col, StepIn<MIX, KPL>& s) {
;   const float* base = qkdv + t * 256;
; #pragma unroll
;   for (int i = 0; i < KPL; i += 4) {
;     const f32x4 a = *(const f32x4*)(base + kg * KPL + i), b = *(const f32x4*)(base + 64 + kg * KPL + i);
;     s.q[i] = a[0]; s.q[i + 1] = a[1]; s.q[i + 2] = a[2]; s.q[i + 3] = a[3];
;     s.k[i] = b[0]; s.k[i + 1] = b[1]; s.k[i + 2] = b[2]; s.k[i + 3] = b[3];
;     if (MIX == 1 || MIX == 2) { const f32x4 d = *(const f32x4*)(base + 128 + kg * KPL + i); s.d[i] = d[0]; s.d[i + 1] = d[1]; s.d[i + 2] = d[2]; s.d[i + 3] = d[3]; }
;   }
;   s.v = base[192 + col];
;   if (MIX == 0) { const f32x4 c = *(const f32x4*)(scal + t * 4); s.a = c[0]; s.be = c[1]; s.qk = c[2]; }
; }
; template <int MIX, int KPL, int KG>
; __device__ __forceinline__ float do_step(const StepIn<MIX, KPL>& s, float (&S)[KPL], const float gam) {
;   if (MIX == 0) {
;     float kS0 = 0.f, kS1 = 0.f, qS0 = 0.f, qS1 = 0.f;
; #pragma unroll
;     for (int i = 0; i < KPL; i += 2) { kS0 += s.k[i] * S[i]; kS1 += s.k[i + 1] * S[i + 1]; qS0 += s.q[i] * S[i]; qS1 += s.q[i + 1] * S[i + 1]; }
;     const float kS = redKG<KG>(kS0 + kS1), qS = redKG<KG>(qS0 + qS1);
;     const float w = s.be * (s.v - s.a * kS);
; #pragma unroll
;     for (int i = 0; i < KPL; ++i) S[i] = s.a * S[i] + s.k[i] * w;
;     return s.a * qS + s.qk * w;
; template <int MIX>
; __device__ __forceinline__ void scan_part(const Params& p, const int layer, const int smp, const int b0, const int bstep, const int bend, const int h, const int part, char* lds, const int tid) {
;     ...
;       for (int t = 0; t < ntok; t += 2) {
;         load_step<MIX, KPL>(qkdv, scal, t + 1, kg, col, sb);
;         __builtin_amdgcn_sched_barrier(0);
;         const float oa = do_step<MIX, KPL, KG>(sa, S, gam);
;         osave = (kg == (t & (KG - 1))) ? oa : osave;
;         load_step<MIX, KPL>(qkdv, scal, min(t + 2, ntok - 1), kg, col, sa);
;         __builtin_amdgcn_sched_barrier(0);
;         const float ob = do_step<MIX, KPL, KG>(sb, S, gam);
;         osave = (kg == ((t + 1) & (KG - 1))) ? ob : osave;
;         if (((t + 2) & (KG - 1)) == 0) obuf[(t + 2 - KG + kg) * CW + col] = osave;
	v_pk_mul_f32 v[192:193], v[178:179], v[104:105]
	v_pk_fma_f32 v[192:193], v[180:181], v[102:103], v[192:193]
	v_add_f32_e32 v203, v192, v193
	ds_read_b128 v[184:187], v211 offset:11520
	v_add_f32_e32 v222, v200, v201
	v_add_f32_dpp v203, v203, v203 quad_perm:[1,0,3,2] row_mask:0xf bank_mask:0xf bound_ctrl:1
	s_waitcnt lgkmcnt(1)
	v_pk_mul_f32 v[194:195], v[104:105], v[158:159] op_sel_hi:[1,0]
	v_pk_mul_f32 v[196:197], v[102:103], v[158:159] op_sel_hi:[1,0]
	v_add_f32_dpp v203, v203, v203 quad_perm:[2,3,0,1] row_mask:0xf bank_mask:0xf bound_ctrl:1
	v_pk_mul_f32 v[200:201], v[80:81], v[104:105]
	v_pk_fma_f32 v[200:201], v[82:83], v[102:103], v[200:201]
	v_add_f32_dpp v203, v203, v203 row_half_mirror row_mask:0xf bank_mask:0xf bound_ctrl:1
	ds_read_b64 v[168:169], v213 offset:37040
	ds_read_b32 v190, v212 offset:12032
	v_add_f32_dpp v203, v203, v203 row_mirror row_mask:0xf bank_mask:0xf bound_ctrl:1
	v_fma_f32 v204, -v158, v203, v189
	v_mul_f32_e32 v206, v159, v204
	v_pk_fma_f32 v[104:105], v[178:179], v[206:207], v[194:195] op_sel_hi:[1,0,1]
	v_pk_fma_f32 v[102:103], v[180:181], v[206:207], v[196:197] op_sel_hi:[1,0,1]
	s_waitcnt lgkmcnt(2)
	v_pk_mul_f32 v[192:193], v[184:185], v[104:105]
	v_pk_fma_f32 v[192:193], v[186:187], v[102:103], v[192:193]
	ds_read_b128 v[84:87], v211 offset:10240
	v_add_f32_e32 v203, v192, v193
	ds_read_b128 v[92:95], v211 offset:12544
	v_cndmask_b32_e64 v223, v215, v216, s[52:53]
	v_add_f32_dpp v203, v203, v203 quad_perm:[1,0,3,2] row_mask:0xf bank_mask:0xf bound_ctrl:1
	v_cndmask_b32_e64 v224, v216, v215, s[52:53]
	v_add_f32_e32 v215, v198, v199
	v_add_f32_dpp v203, v203, v203 quad_perm:[2,3,0,1] row_mask:0xf bank_mask:0xf bound_ctrl:1
	s_waitcnt lgkmcnt(2)
	v_pk_mul_f32 v[194:195], v[104:105], v[168:169] op_sel_hi:[1,0]
	v_pk_mul_f32 v[196:197], v[102:103], v[168:169] op_sel_hi:[1,0]
	v_add_f32_dpp v203, v203, v203 row_half_mirror row_mask:0xf bank_mask:0xf bound_ctrl:1
	ds_read_b64 v[106:107], v213 offset:37056
	ds_read_b32 v182, v212 offset:13056
	v_add_f32_dpp v203, v203, v203 row_mirror row_mask:0xf bank_mask:0xf bound_ctrl:1
	v_fma_f32 v204, -v168, v203, v190
	s_waitcnt lgkmcnt(2)
	v_pk_mul_f32 v[198:199], v[84:85], v[104:105]
	v_mul_f32_e32 v206, v169, v204
	v_pk_fma_f32 v[198:199], v[86:87], v[102:103], v[198:199]
	v_pk_fma_f32 v[104:105], v[184:185], v[206:207], v[194:195] op_sel_hi:[1,0,1]
	v_pk_fma_f32 v[102:103], v[186:187], v[206:207], v[196:197] op_sel_hi:[1,0,1]
	v_pk_mul_f32 v[192:193], v[92:93], v[104:105]
	v_pk_fma_f32 v[192:193], v[94:95], v[102:103], v[192:193]
	ds_read_b128 v[88:91], v211 offset:11264
	v_add_f32_e32 v203, v192, v193
	ds_read_b128 v[174:177], v211 offset:13568
	v_add_f32_e32 v216, v200, v201
	v_add_f32_dpp v203, v203, v203 quad_perm:[1,0,3,2] row_mask:0xf bank_mask:0xf bound_ctrl:1
	s_waitcnt lgkmcnt(2)
	v_pk_mul_f32 v[194:195], v[104:105], v[106:107] op_sel_hi:[1,0]
	v_pk_mul_f32 v[196:197], v[102:103], v[106:107] op_sel_hi:[1,0]
	v_add_f32_dpp v203, v203, v203 quad_perm:[2,3,0,1] row_mask:0xf bank_mask:0xf bound_ctrl:1
	ds_read_b64 v[154:155], v213 offset:37072
	ds_read_b32 v188, v212 offset:14080
	v_add_f32_dpp v203, v203, v203 row_half_mirror row_mask:0xf bank_mask:0xf bound_ctrl:1
	ds_read_b128 v[76:79], v211 offset:12288
	ds_read_b128 v[178:181], v211 offset:14592
	v_add_f32_dpp v203, v203, v203 row_mirror row_mask:0xf bank_mask:0xf bound_ctrl:1
	v_fma_f32 v204, -v106, v203, v182
	s_waitcnt lgkmcnt(4)
	v_pk_mul_f32 v[200:201], v[88:89], v[104:105]
	v_mul_f32_e32 v206, v107, v204
	v_pk_fma_f32 v[200:201], v[90:91], v[102:103], v[200:201]
	v_pk_fma_f32 v[104:105], v[92:93], v[206:207], v[194:195] op_sel_hi:[1,0,1]
	v_pk_fma_f32 v[102:103], v[94:95], v[206:207], v[196:197] op_sel_hi:[1,0,1]
	v_pk_mul_f32 v[192:193], v[174:175], v[104:105]
	v_pk_fma_f32 v[192:193], v[176:177], v[102:103], v[192:193]
	v_add_f32_e32 v203, v192, v193
	v_cndmask_b32_e64 v225, v217, v218, s[52:53]
	v_cndmask_b32_e64 v226, v218, v217, s[52:53]
	v_add_f32_dpp v203, v203, v203 quad_perm:[1,0,3,2] row_mask:0xf bank_mask:0xf bound_ctrl:1
	v_add_f32_e32 v217, v198, v199
	s_waitcnt lgkmcnt(0)
	v_pk_mul_f32 v[198:199], v[76:77], v[104:105]
	v_add_f32_dpp v203, v203, v203 quad_perm:[2,3,0,1] row_mask:0xf bank_mask:0xf bound_ctrl:1
	v_pk_mul_f32 v[194:195], v[104:105], v[154:155] op_sel_hi:[1,0]
	v_pk_fma_f32 v[198:199], v[78:79], v[102:103], v[198:199]
	v_add_f32_dpp v203, v203, v203 row_half_mirror row_mask:0xf bank_mask:0xf bound_ctrl:1
	v_pk_mul_f32 v[196:197], v[102:103], v[154:155] op_sel_hi:[1,0]
	v_add_f32_dpp v227, v224, v223 quad_perm:[1,0,3,2] row_mask:0xf bank_mask:0xf bound_ctrl:1
	v_add_f32_dpp v203, v203, v203 row_mirror row_mask:0xf bank_mask:0xf bound_ctrl:1
	v_fma_f32 v204, -v154, v203, v188
	v_mul_f32_e32 v206, v155, v204
	v_pk_fma_f32 v[104:105], v[174:175], v[206:207], v[194:195] op_sel_hi:[1,0,1]
	v_add_f32_dpp v228, v226, v225 quad_perm:[1,0,3,2] row_mask:0xf bank_mask:0xf bound_ctrl:1
	v_pk_fma_f32 v[102:103], v[176:177], v[206:207], v[196:197] op_sel_hi:[1,0,1]
	v_pk_mul_f32 v[192:193], v[178:179], v[104:105]
	v_cndmask_b32_e64 v223, v227, v228, s[54:55]
	v_cndmask_b32_e64 v224, v228, v227, s[54:55]
	ds_read_b64 v[158:159], v213 offset:37088
	ds_read_b32 v189, v212 offset:15104
	v_pk_fma_f32 v[192:193], v[180:181], v[102:103], v[192:193]
	ds_read_b128 v[80:83], v211 offset:13312
	v_add_f32_e32 v203, v192, v193
	v_add_f32_dpp v225, v224, v223 quad_perm:[2,3,0,1] row_mask:0xf bank_mask:0xf bound_ctrl:1
	ds_read_b128 v[184:187], v211 offset:15616
	v_add_f32_dpp v203, v203, v203 quad_perm:[1,0,3,2] row_mask:0xf bank_mask:0xf bound_ctrl:1
	v_add_f32_dpp v226, v225, v225 row_ror:4 row_mask:0xf bank_mask:0xf bound_ctrl:1
	v_cndmask_b32_e64 v223, v219, v220, s[52:53]
	v_add_f32_dpp v203, v203, v203 quad_perm:[2,3,0,1] row_mask:0xf bank_mask:0xf bound_ctrl:1
	v_add_f32_dpp v205, v226, v226 row_ror:8 row_mask:0xf bank_mask:0xf bound_ctrl:1
	v_cndmask_b32_e64 v224, v220, v219, s[52:53]
	v_cndmask_b32_e64 v225, v221, v222, s[52:53]
	v_cndmask_b32_e64 v226, v222, v221, s[52:53]
	v_add_f32_dpp v203, v203, v203 row_half_mirror row_mask:0xf bank_mask:0xf bound_ctrl:1
	v_add_f32_dpp v227, v224, v223 quad_perm:[1,0,3,2] row_mask:0xf bank_mask:0xf bound_ctrl:1
	v_add_f32_dpp v228, v226, v225 quad_perm:[1,0,3,2] row_mask:0xf bank_mask:0xf bound_ctrl:1
	v_add_f32_dpp v203, v203, v203 row_mirror row_mask:0xf bank_mask:0xf bound_ctrl:1
	v_cndmask_b32_e64 v223, v227, v228, s[54:55]
	v_cndmask_b32_e64 v224, v228, v227, s[54:55]
	v_add_f32_e32 v218, v200, v201
	s_waitcnt lgkmcnt(0)
; template <int KG> __device__ __forceinline__ float redKG(float x) { x = red8d(x); if (KG == 16) x += dpp_rm(x); return x; }
; template <int MIX, int KPL, int KG>
; __device__ __forceinline__ float do_step(const StepIn<MIX, KPL>& s, float (&S)[KPL], const float gam) {
;   if (MIX == 0) {
;     float kS0 = 0.f, kS1 = 0.f, qS0 = 0.f, qS1 = 0.f;
; #pragma unroll
;     for (int i = 0; i < KPL; i += 2) { kS0 += s.k[i] * S[i]; kS1 += s.k[i + 1] * S[i + 1]; qS0 += s.q[i] * S[i]; qS1 += s.q[i + 1] * S[i + 1]; }
;     const float kS = redKG<KG>(kS0 + kS1), qS = redKG<KG>(qS0 + qS1);
;     const float w = s.be * (s.v - s.a * kS);
; #pragma unroll
;     for (int i = 0; i < KPL; ++i) S[i] = s.a * S[i] + s.k[i] * w;
;     return s.a * qS + s.qk * w;
; template <int MIX>
; __device__ __forceinline__ void scan_part(const Params& p, const int layer, const int smp, const int b0, const int bstep, const int bend, const int h, const int part, char* lds, const int tid) {
;     ...
;       for (int t = 0; t < ntok; t += 2) {
;         load_step<MIX, KPL>(qkdv, scal, t + 1, kg, col, sb);
;         __builtin_amdgcn_sched_barrier(0);
;         const float oa = do_step<MIX, KPL, KG>(sa, S, gam);
;         osave = (kg == (t & (KG - 1))) ? oa : osave;
;         load_step<MIX, KPL>(qkdv, scal, min(t + 2, ntok - 1), kg, col, sa);
;         __builtin_amdgcn_sched_barrier(0);
;         const float ob = do_step<MIX, KPL, KG>(sb, S, gam);
;         osave = (kg == ((t + 1) & (KG - 1))) ? ob : osave;
;         if (((t + 2) & (KG - 1)) == 0) obuf[(t + 2 - KG + kg) * CW + col] = osave;
	v_fma_f32 v204, -v158, v203, v189
	v_pk_mul_f32 v[200:201], v[80:81], v[104:105]
	v_pk_mul_f32 v[194:195], v[104:105], v[158:159] op_sel_hi:[1,0]
	v_mul_f32_e32 v206, v159, v204
	v_pk_fma_f32 v[200:201], v[82:83], v[102:103], v[200:201]
	v_pk_mul_f32 v[196:197], v[102:103], v[158:159] op_sel_hi:[1,0]
	v_pk_fma_f32 v[104:105], v[178:179], v[206:207], v[194:195] op_sel_hi:[1,0,1]
	v_add_f32_dpp v225, v224, v223 quad_perm:[2,3,0,1] row_mask:0xf bank_mask:0xf bound_ctrl:1
	v_pk_fma_f32 v[102:103], v[180:181], v[206:207], v[196:197] op_sel_hi:[1,0,1]
	v_pk_mul_f32 v[192:193], v[184:185], v[104:105]
	ds_read_b64 v[168:169], v213 offset:37104
	ds_read_b32 v190, v212 offset:16128
	v_pk_fma_f32 v[192:193], v[186:187], v[102:103], v[192:193]
	ds_read_b128 v[84:87], v211 offset:14336
	v_add_f32_e32 v203, v192, v193
	v_add_f32_dpp v226, v225, v225 row_ror:4 row_mask:0xf bank_mask:0xf bound_ctrl:1
	ds_read_b128 v[88:91], v211 offset:15360
	v_add_f32_dpp v203, v203, v203 quad_perm:[1,0,3,2] row_mask:0xf bank_mask:0xf bound_ctrl:1
	v_add_f32_dpp v208, v226, v226 row_ror:8 row_mask:0xf bank_mask:0xf bound_ctrl:1
	v_cndmask_b32_e64 v223, v215, v216, s[52:53]
	v_cndmask_b32_e64 v224, v216, v215, s[52:53]
	v_cndmask_b32_e64 v225, v217, v218, s[52:53]
	v_cndmask_b32_e64 v226, v218, v217, s[52:53]
	v_add_f32_dpp v203, v203, v203 quad_perm:[2,3,0,1] row_mask:0xf bank_mask:0xf bound_ctrl:1
	v_add_f32_dpp v227, v224, v223 quad_perm:[1,0,3,2] row_mask:0xf bank_mask:0xf bound_ctrl:1
	v_add_f32_dpp v228, v226, v225 quad_perm:[1,0,3,2] row_mask:0xf bank_mask:0xf bound_ctrl:1
	v_cndmask_b32_e64 v223, v227, v228, s[54:55]
	v_cndmask_b32_e64 v224, v228, v227, s[54:55]
	v_add_f32_dpp v203, v203, v203 row_half_mirror row_mask:0xf bank_mask:0xf bound_ctrl:1
	v_add_f32_e32 v219, v198, v199
	v_add_f32_dpp v225, v224, v223 quad_perm:[2,3,0,1] row_mask:0xf bank_mask:0xf bound_ctrl:1
	v_add_f32_dpp v203, v203, v203 row_mirror row_mask:0xf bank_mask:0xf bound_ctrl:1
	s_waitcnt lgkmcnt(0)
	v_fma_f32 v204, -v168, v203, v190
	v_pk_mul_f32 v[198:199], v[84:85], v[104:105]
	v_pk_mul_f32 v[194:195], v[104:105], v[168:169] op_sel_hi:[1,0]
	v_mul_f32_e32 v206, v169, v204
	v_add_f32_dpp v226, v225, v225 row_ror:4 row_mask:0xf bank_mask:0xf bound_ctrl:1
	v_add_f32_e32 v220, v200, v201
	v_pk_fma_f32 v[198:199], v[86:87], v[102:103], v[198:199]
	v_pk_mul_f32 v[196:197], v[102:103], v[168:169] op_sel_hi:[1,0]
	v_pk_fma_f32 v[104:105], v[184:185], v[206:207], v[194:195] op_sel_hi:[1,0,1]
	v_pk_fma_f32 v[102:103], v[186:187], v[206:207], v[196:197] op_sel_hi:[1,0,1]
	v_pk_mul_f32 v[200:201], v[88:89], v[104:105]
	v_pk_fma_f32 v[200:201], v[90:91], v[102:103], v[200:201]
	v_add_f32_dpp v209, v226, v226 row_ror:8 row_mask:0xf bank_mask:0xf bound_ctrl:1
	v_add_f32_e32 v221, v198, v199
	v_add_f32_e32 v222, v200, v201
	v_cndmask_b32_e64 v223, v219, v220, s[52:53]
	v_cndmask_b32_e64 v224, v220, v219, s[52:53]
	v_cndmask_b32_e64 v225, v221, v222, s[52:53]
	v_cndmask_b32_e64 v226, v222, v221, s[52:53]
	v_add_f32_dpp v227, v224, v223 quad_perm:[1,0,3,2] row_mask:0xf bank_mask:0xf bound_ctrl:1
	ds_read_b128 v[92:95], v211 offset:16640
	v_add_f32_dpp v228, v226, v225 quad_perm:[1,0,3,2] row_mask:0xf bank_mask:0xf bound_ctrl:1
	v_cndmask_b32_e64 v223, v227, v228, s[54:55]
	v_cndmask_b32_e64 v224, v228, v227, s[54:55]
	ds_read_b64 v[106:107], v213 offset:37120
	ds_read_b32 v182, v212 offset:17152
	v_add_f32_dpp v225, v224, v223 quad_perm:[2,3,0,1] row_mask:0xf bank_mask:0xf bound_ctrl:1
	ds_read_b128 v[76:79], v211 offset:16384
	ds_read_b128 v[174:177], v211 offset:17664
	v_add_f32_dpp v226, v225, v225 row_ror:4 row_mask:0xf bank_mask:0xf bound_ctrl:1
	ds_read_b64 v[154:155], v213 offset:37136
	ds_read_b32 v188, v212 offset:18176
	v_add_f32_dpp v210, v226, v226 row_ror:8 row_mask:0xf bank_mask:0xf bound_ctrl:1
	ds_read_b128 v[80:83], v211 offset:17408
	ds_write_b32 v214, v205 offset:32768
	ds_write_b32 v214, v208 offset:33024
	ds_write_b32 v214, v209 offset:33280
	ds_write_b32 v214, v210 offset:33536
	v_add_u32_e32 v211, 0x4000, v211
	v_add_u32_e32 v212, 0x4000, v212
	v_add_u32_e32 v213, 0x100, v213
	v_add_u32_e32 v214, 0x400, v214
	s_sub_i32 s50, s50, 1
	s_cmp_lg_u32 s50, 0
	s_cbranch_scc1 .Lscan0p_blk
